# group start stagger s_sleep 12 per index step (fine tuning between 10 and 14)
# speedup vs baseline: 1.0166x; 1.0166x over previous
; __device__ __forceinline__ void mk_p3(const Ptrs& P, LAS unsigned char* lds, int tid, int wave, int lane, int bx, int G, bool dry) {
;     ...
;         { bool pre = false; for (int u = bx; u < NB * 32 * 4; u += G) pre = attn_unit(P, lds, u, tid, wave, lane, pre, u + G < NB * 32 * 4 ? u + G : -1); }
.Lstg_loop:
	s_cmp_eq_u32 vcc_lo, 0
	s_cbranch_scc1 .Lstg_done
	s_sleep 12
	s_sub_u32 vcc_lo, vcc_lo, 1
	s_branch .Lstg_loop
